# NSA selected loop: union mask cached in SGPRs (s_ff1 next-tile scan, no LDS round trip) and per-token select words cached in a VGPR quad, on v_m23
# baseline (speedup 1.0000x reference)
.LBB0_394:
	v_lshlrev_b32_e32 v9, 16, v82
	v_lshlrev_b32_e32 v8, 16, v86
	v_mov_b32_e32 v24, v78
	v_mov_b32_e32 v25, v74
	v_pk_mul_f32 v[24:25], v[24:25], v[8:9]
	v_and_b32_e32 v11, 0xffff0000, v82
	v_sub_f32_e32 v0, v24, v25
	v_mov_b32_e32 v24, v74
	v_mov_b32_e32 v25, v78
	v_and_b32_e32 v10, 0xffff0000, v86
	v_pk_mul_f32 v[8:9], v[24:25], v[8:9]
	v_mov_b32_e32 v74, v79
	v_add_f32_e32 v5, v8, v9
	v_cmp_gt_u32_e32 vcc, 32, v185
	v_pk_mul_f32 v[8:9], v[74:75], v[10:11]
	v_mov_b32_e32 v78, v75
	v_cndmask_b32_e32 v0, v5, v0, vcc
	v_sub_f32_e32 v5, v8, v9
	v_pk_mul_f32 v[8:9], v[78:79], v[10:11]
	v_lshlrev_b32_e32 v13, 16, v83
	v_lshlrev_b32_e32 v12, 16, v87
	v_add_f32_e32 v7, v9, v8
	v_mov_b32_e32 v8, v80
	v_mov_b32_e32 v9, v76
	v_pk_mul_f32 v[8:9], v[8:9], v[12:13]
	v_cndmask_b32_e32 v5, v7, v5, vcc
	v_sub_f32_e32 v7, v8, v9
	v_mov_b32_e32 v8, v76
	v_mov_b32_e32 v9, v80
	v_pk_mul_f32 v[8:9], v[8:9], v[12:13]
	v_and_b32_e32 v15, 0xffff0000, v83
	v_and_b32_e32 v14, 0xffff0000, v87
	v_add_f32_e32 v8, v9, v8
	v_mov_b32_e32 v76, v81
	v_cndmask_b32_e32 v7, v8, v7, vcc
	v_pk_mul_f32 v[8:9], v[76:77], v[14:15]
	v_mov_b32_e32 v80, v77
	v_sub_f32_e32 v10, v8, v9
	v_pk_mul_f32 v[8:9], v[80:81], v[14:15]
	v_lshlrev_b32_e32 v17, 16, v84
	v_add_f32_e32 v8, v9, v8
	v_lshlrev_b32_e32 v16, 16, v88
	v_cndmask_b32_e32 v10, v8, v10, vcc
	v_mov_b32_e32 v8, v70
	v_mov_b32_e32 v9, v66
	v_pk_mul_f32 v[8:9], v[8:9], v[16:17]
	v_and_b32_e32 v19, 0xffff0000, v84
	v_sub_f32_e32 v11, v8, v9
	v_mov_b32_e32 v8, v66
	v_mov_b32_e32 v9, v70
	v_pk_mul_f32 v[8:9], v[8:9], v[16:17]
	v_and_b32_e32 v18, 0xffff0000, v88
	v_add_f32_e32 v8, v9, v8
	v_mov_b32_e32 v66, v71
	v_cndmask_b32_e32 v11, v8, v11, vcc
	v_pk_mul_f32 v[8:9], v[66:67], v[18:19]
	v_mov_b32_e32 v70, v67
	v_sub_f32_e32 v12, v8, v9
	v_pk_mul_f32 v[8:9], v[70:71], v[18:19]
	v_lshlrev_b32_e32 v21, 16, v85
	v_add_f32_e32 v8, v9, v8
	v_lshlrev_b32_e32 v20, 16, v89
	v_cndmask_b32_e32 v12, v8, v12, vcc
	v_mov_b32_e32 v8, v72
	v_mov_b32_e32 v9, v68
	v_pk_mul_f32 v[8:9], v[8:9], v[20:21]
	v_and_b32_e32 v23, 0xffff0000, v85
	v_sub_f32_e32 v13, v8, v9
	v_mov_b32_e32 v8, v68
	v_mov_b32_e32 v9, v72
	v_pk_mul_f32 v[8:9], v[8:9], v[20:21]
	v_and_b32_e32 v22, 0xffff0000, v89
	v_add_f32_e32 v8, v9, v8
	v_mov_b32_e32 v68, v73
	v_cndmask_b32_e32 v13, v8, v13, vcc
	v_pk_mul_f32 v[8:9], v[68:69], v[22:23]
	v_mov_b32_e32 v72, v69
	v_sub_f32_e32 v14, v8, v9
	v_pk_mul_f32 v[8:9], v[72:73], v[22:23]
	s_lshl_b32 s46, s75, 3
	v_add_f32_e32 v8, v9, v8
	s_add_i32 s46, s46, s74
	v_cndmask_b32_e32 v8, v8, v14, vcc
	v_mov_b32_e32 v81, 0
	v_cvt_pk_bf16_f32 v142, v0, v5
	v_cvt_pk_bf16_f32 v143, v7, v10
	v_cvt_pk_bf16_f32 v144, v11, v12
	v_cvt_pk_bf16_f32 v145, v13, v8
	s_cmp_gt_u32 s94, s80
	v_mov_b32_e32 v80, v81
	v_mov_b32_e32 v79, v81
	v_mov_b32_e32 v78, v81
	v_mov_b32_e32 v77, v81
	v_mov_b32_e32 v76, v81
	v_mov_b32_e32 v75, v81
	v_mov_b32_e32 v74, v81
	v_mov_b32_e32 v73, v81
	v_mov_b32_e32 v72, v81
	v_mov_b32_e32 v71, v81
	v_mov_b32_e32 v70, v81
	v_mov_b32_e32 v69, v81
	v_mov_b32_e32 v68, v81
	v_mov_b32_e32 v67, v81
	v_mov_b32_e32 v66, v81
	s_waitcnt vmcnt(6)
	v_mov_b32_e32 v97, v81
	v_mov_b32_e32 v96, v81
	v_mov_b32_e32 v95, v81
	v_mov_b32_e32 v94, v81
	v_mov_b32_e32 v93, v81
	v_mov_b32_e32 v92, v81
	v_mov_b32_e32 v91, v81
	v_mov_b32_e32 v90, v81
	v_mov_b32_e32 v89, v81
	v_mov_b32_e32 v88, v81
	v_mov_b32_e32 v87, v81
	v_mov_b32_e32 v86, v81
	v_mov_b32_e32 v85, v81
	v_mov_b32_e32 v84, v81
	v_mov_b32_e32 v83, v81
	v_mov_b32_e32 v82, v81
	v_mov_b32_e32 v201, v81
	s_cbranch_scc1 .LBB0_410
	v_lshrrev_b32_e32 v5, 3, v6
	v_lshlrev_b32_e32 v166, 4, v6
	v_and_b32_e32 v168, 4, v5
	v_ashrrev_i32_e32 v5, 31, v4
	v_mov_b32_e32 v201, 0
	v_lshlrev_b32_e32 v0, 4, v184
	ds_read_b128 v[226:229], v0 offset:49152
	ds_read_b128 v[230:233], v1 offset:49664
	s_waitcnt lgkmcnt(0)
	v_readfirstlane_b32 s2, v230
	v_readfirstlane_b32 s3, v231
	v_readfirstlane_b32 s98, v232
	v_readfirstlane_b32 s99, v233
	v_and_b32_e32 v167, 0x3f0, v166
	s_mov_b32 s49, 0
	v_mov_b32_e32 v170, 0xf149f2ca
	v_lshlrev_b64 v[162:163], 1, v[2:3]
	v_lshlrev_b64 v[164:165], 1, v[4:5]
	v_mov_b32_e32 v82, 0
	v_mov_b32_e32 v83, v201
	v_mov_b32_e32 v84, v201
	v_mov_b32_e32 v85, v201
	v_mov_b32_e32 v86, v201
	v_mov_b32_e32 v87, v201
	v_mov_b32_e32 v88, v201
	v_mov_b32_e32 v89, v201
	v_mov_b32_e32 v90, v201
	v_mov_b32_e32 v91, v201
	v_mov_b32_e32 v92, v201
	v_mov_b32_e32 v93, v201
	v_mov_b32_e32 v94, v201
	v_mov_b32_e32 v95, v201
	v_mov_b32_e32 v96, v201
	v_mov_b32_e32 v97, v201
	v_mov_b32_e32 v66, v201
	v_mov_b32_e32 v67, v201
	v_mov_b32_e32 v68, v201
	v_mov_b32_e32 v69, v201
	v_mov_b32_e32 v70, v201
	v_mov_b32_e32 v71, v201
	v_mov_b32_e32 v72, v201
	v_mov_b32_e32 v73, v201
	v_mov_b32_e32 v74, v201
	v_mov_b32_e32 v75, v201
	v_mov_b32_e32 v76, v201
	v_mov_b32_e32 v77, v201
	v_mov_b32_e32 v78, v201
	v_mov_b32_e32 v79, v201
	v_mov_b32_e32 v80, v201
	v_mov_b32_e32 v81, v201
	s_waitcnt vmcnt(0)
	ds_write_b128 v166, v[98:101]
	ds_write_b128 v166, v[102:105] offset:4096
	ds_write_b128 v166, v[106:109] offset:8192
	ds_write_b128 v166, v[110:113] offset:12288
	s_mov_b32 s101, 1

.Lmy_wd:
	v_cmp_ne_u32_e64 s[40:41], 0, v2
	s_mov_b64 vcc, s[40:41]
	s_cbranch_vccz .LBB0_408
